# residual epilogues (FFN-out, FFN2-out, mix-out, xattn-out): bf16 XB copy stored as two dwordx4 per row block via v_permlane16_swap (was four dwordx2)
# speedup vs baseline: 1.0488x; 1.0098x over previous
.Lkx_246:
	s_mov_b32 s2, 0x18000
	v_add3_u32 v144, v134, v135, s2
	v_add3_u32 v135, v132, v135, s81
	ds_read_b128 v[128:131], v144
	ds_read_b128 v[136:139], v144 offset:2048
	ds_read_b128 v[140:143], v144 offset:4096
	ds_read_b128 v[146:149], v144 offset:6144
	ds_read_b128 v[154:157], v135
	ds_read_b128 v[158:161], v135 offset:2048
	ds_read_b128 v[162:165], v135 offset:4096
	ds_read_b128 v[166:169], v135 offset:6144
	ds_read_b128 v[170:173], v135 offset:8192
	ds_read_b128 v[174:177], v135 offset:10240
	ds_read_b128 v[178:181], v135 offset:12288
	ds_read_b128 v[182:185], v135 offset:14336
	s_waitcnt lgkmcnt(7)
	v_mfma_f32_16x16x32_bf16 v[120:123], v[136:139], v[154:157], v[120:123]
	v_mfma_f32_16x16x32_bf16 v[116:119], v[140:143], v[154:157], v[116:119]
	v_mfma_f32_16x16x32_bf16 v[112:115], v[146:149], v[154:157], v[112:115]
	s_waitcnt lgkmcnt(6)
	v_mfma_f32_16x16x32_bf16 v[108:111], v[128:131], v[158:161], v[108:111]
	v_mfma_f32_16x16x32_bf16 v[104:107], v[136:139], v[158:161], v[104:107]
	v_mfma_f32_16x16x32_bf16 v[100:103], v[140:143], v[158:161], v[100:103]
	v_mfma_f32_16x16x32_bf16 v[96:99], v[146:149], v[158:161], v[96:99]
	s_waitcnt lgkmcnt(5)
	v_mfma_f32_16x16x32_bf16 v[92:95], v[128:131], v[162:165], v[92:95]
	v_mfma_f32_16x16x32_bf16 v[84:87], v[136:139], v[162:165], v[84:87]
	v_mfma_f32_16x16x32_bf16 v[80:83], v[140:143], v[162:165], v[80:83]
	v_mfma_f32_16x16x32_bf16 v[76:79], v[146:149], v[162:165], v[76:79]
	s_waitcnt lgkmcnt(4)
	v_mfma_f32_16x16x32_bf16 v[72:75], v[128:131], v[166:169], v[72:75]
	v_mfma_f32_16x16x32_bf16 v[68:71], v[136:139], v[166:169], v[68:71]
	v_mfma_f32_16x16x32_bf16 v[64:67], v[140:143], v[166:169], v[64:67]
	v_mfma_f32_16x16x32_bf16 v[60:63], v[146:149], v[166:169], v[60:63]
	v_mfma_f32_16x16x32_bf16 v[124:127], v[128:131], v[154:157], v[124:127]
	v_add3_u32 v134, v134, v133, s2
	v_add3_u32 v144, v132, v133, s81
	ds_read_b128 v[154:157], v134
	ds_read_b128 v[158:161], v134 offset:2048
	ds_read_b128 v[162:165], v134 offset:4096
	ds_read_b128 v[166:169], v134 offset:6144
	ds_read_b128 v[132:135], v144
	ds_read_b128 v[186:189], v144 offset:2048
	ds_read_b128 v[206:209], v144 offset:4096
	ds_read_b128 v[216:219], v144 offset:6144
	s_waitcnt lgkmcnt(11)
	v_mfma_f32_16x16x32_bf16 v[56:59], v[128:131], v[170:173], v[56:59]
	v_mfma_f32_16x16x32_bf16 v[52:55], v[136:139], v[170:173], v[52:55]
	v_mfma_f32_16x16x32_bf16 v[48:51], v[140:143], v[170:173], v[48:51]
	v_mfma_f32_16x16x32_bf16 v[44:47], v[146:149], v[170:173], v[44:47]
	s_waitcnt lgkmcnt(10)
	v_mfma_f32_16x16x32_bf16 v[40:43], v[128:131], v[174:177], v[40:43]
	v_mfma_f32_16x16x32_bf16 v[36:39], v[136:139], v[174:177], v[36:39]
	v_mfma_f32_16x16x32_bf16 v[32:35], v[140:143], v[174:177], v[32:35]
	v_mfma_f32_16x16x32_bf16 v[28:31], v[146:149], v[174:177], v[28:31]
	s_waitcnt lgkmcnt(9)
	v_mfma_f32_16x16x32_bf16 v[24:27], v[128:131], v[178:181], v[24:27]
	v_mfma_f32_16x16x32_bf16 v[20:23], v[136:139], v[178:181], v[20:23]
	v_mfma_f32_16x16x32_bf16 v[16:19], v[140:143], v[178:181], v[16:19]
	v_mfma_f32_16x16x32_bf16 v[12:15], v[146:149], v[178:181], v[12:15]
	s_waitcnt lgkmcnt(8)
	v_mfma_f32_16x16x32_bf16 v[8:11], v[128:131], v[182:185], v[8:11]
	v_mfma_f32_16x16x32_bf16 v[4:7], v[136:139], v[182:185], v[4:7]
	v_mfma_f32_16x16x32_bf16 v[0:3], v[140:143], v[182:185], v[0:3]
	v_mfma_f32_16x16x32_bf16 v[128:131], v[146:149], v[182:185], v[88:91]
	ds_read_b128 v[136:139], v144 offset:8192
	ds_read_b128 v[140:143], v144 offset:10240
	ds_read_b128 v[146:149], v144 offset:12288
	ds_read_b128 v[170:173], v144 offset:14336
	s_waitcnt lgkmcnt(7)
	v_mfma_f32_16x16x32_bf16 v[120:123], v[158:161], v[132:135], v[120:123]
	s_waitcnt lgkmcnt(6)
	v_mfma_f32_16x16x32_bf16 v[108:111], v[154:157], v[186:189], v[108:111]
	v_mfma_f32_16x16x32_bf16 v[104:107], v[158:161], v[186:189], v[104:107]
	v_mfma_f32_16x16x32_bf16 v[100:103], v[162:165], v[186:189], v[100:103]
	v_mfma_f32_16x16x32_bf16 v[96:99], v[166:169], v[186:189], v[96:99]
	s_waitcnt lgkmcnt(5)
	v_mfma_f32_16x16x32_bf16 v[92:95], v[154:157], v[206:209], v[92:95]
	v_mfma_f32_16x16x32_bf16 v[88:91], v[158:161], v[206:209], v[84:87]
	v_mfma_f32_16x16x32_bf16 v[84:87], v[162:165], v[206:209], v[80:83]
	v_mfma_f32_16x16x32_bf16 v[80:83], v[166:169], v[206:209], v[76:79]
	s_waitcnt lgkmcnt(4)
	v_mfma_f32_16x16x32_bf16 v[76:79], v[154:157], v[216:219], v[72:75]
	v_mfma_f32_16x16x32_bf16 v[72:75], v[158:161], v[216:219], v[68:71]
	v_mfma_f32_16x16x32_bf16 v[68:71], v[162:165], v[216:219], v[64:67]
	v_mfma_f32_16x16x32_bf16 v[64:67], v[166:169], v[216:219], v[60:63]
	v_mfma_f32_16x16x32_bf16 v[124:127], v[154:157], v[132:135], v[124:127]
	v_mfma_f32_16x16x32_bf16 v[174:177], v[162:165], v[132:135], v[116:119]
	v_mfma_f32_16x16x32_bf16 v[132:135], v[166:169], v[132:135], v[112:115]
	s_nop 2
	v_mov_b32_e32 v112, v190
	s_lshl_b32 s2, s22, 8
	s_waitcnt lgkmcnt(3)
	v_mfma_f32_16x16x32_bf16 v[60:63], v[154:157], v[136:139], v[56:59]
	v_ashrrev_i32_e32 v113, 1, v112
	s_lshl_b32 s3, s18, 8
	v_bfe_u32 v144, v112, 6, 2
	v_mfma_f32_16x16x32_bf16 v[56:59], v[158:161], v[136:139], v[52:55]
	v_bfe_u32 v151, v112, 4, 2
	v_mfma_f32_16x16x32_bf16 v[52:55], v[162:165], v[136:139], v[48:51]
	v_mfma_f32_16x16x32_bf16 v[48:51], v[166:169], v[136:139], v[44:47]
	s_waitcnt lgkmcnt(2)
	v_mfma_f32_16x16x32_bf16 v[44:47], v[154:157], v[140:143], v[40:43]
	v_mfma_f32_16x16x32_bf16 v[40:43], v[158:161], v[140:143], v[36:39]
	v_mfma_f32_16x16x32_bf16 v[36:39], v[162:165], v[140:143], v[32:35]
	v_mfma_f32_16x16x32_bf16 v[32:35], v[166:169], v[140:143], v[28:31]
	s_nop 2
	v_and_b32_e32 v28, 0xffffff80, v113
	v_and_or_b32 v29, v112, 15, s2
	v_add_u32_e32 v114, v29, v28
	s_ashr_i32 s2, s3, 31
	v_lshlrev_b32_e32 v112, 6, v144
	v_lshlrev_b32_e32 v113, 2, v151
	v_ashrrev_i32_e32 v115, 31, v114
	s_waitcnt lgkmcnt(1)
	v_mfma_f32_16x16x32_bf16 v[28:31], v[154:157], v[146:149], v[24:27]
	v_or3_b32 v116, s3, v112, v113
	v_mov_b32_e32 v117, s2
	v_mfma_f32_16x16x32_bf16 v[24:27], v[158:161], v[146:149], v[20:23]
	v_mfma_f32_16x16x32_bf16 v[20:23], v[162:165], v[146:149], v[16:19]
	s_nop 2
	v_lshlrev_b64 v[16:17], 10, v[114:115]
	v_lshl_add_u64 v[112:113], v[116:117], 0, v[16:17]
	v_lshl_add_u64 v[178:179], v[112:113], 2, s[90:91]
	global_load_dwordx4 v[228:231], v[178:179], off
	global_load_dwordx4 v[232:235], v[178:179], off offset:64
	global_load_dwordx4 v[236:239], v[178:179], off offset:128
	global_load_dwordx4 v[240:243], v[178:179], off offset:192
	v_lshlrev_b64 v[112:113], 1, v[112:113]
	v_mfma_f32_16x16x32_bf16 v[16:19], v[166:169], v[146:149], v[12:15]
	s_waitcnt vmcnt(3)
	v_pk_add_f32 v[126:127], v[126:127], v[230:231]
	s_waitcnt lgkmcnt(0)
	v_mfma_f32_16x16x32_bf16 v[12:15], v[154:157], v[170:173], v[8:11]
	v_add_f32_e64 v124, v124, v228
	v_add_f32_e64 v125, v125, v229
	global_store_dwordx4 v[178:179], v[124:127], off
	v_cvt_pk_bf16_f32 v10, v124, v125
	v_cvt_pk_bf16_f32 v11, v126, v127
	v_lshl_add_u64 v[8:9], s[16:17], 0, v[112:113]
	v_mov_b32_e32 v248, v10
	v_mov_b32_e32 v249, v11
	v_mfma_f32_16x16x32_bf16 v[8:11], v[158:161], v[170:173], v[4:7]
	s_waitcnt vmcnt(3)
	v_pk_add_f32 v[138:139], v[122:123], v[234:235]
	s_nop 0
	v_or_b32_e32 v4, 32, v112
	v_mov_b32_e32 v5, v113
	v_lshl_add_u64 v[4:5], s[16:17], 0, v[4:5]
	v_pk_add_f32 v[136:137], v[120:121], v[232:233]
	global_store_dwordx4 v[178:179], v[136:139], off offset:64
	v_cvt_pk_bf16_f32 v6, v136, v137
	v_cvt_pk_bf16_f32 v7, v138, v139
	v_mov_b32_e32 v250, v6
	v_mov_b32_e32 v251, v7
	v_mfma_f32_16x16x32_bf16 v[4:7], v[162:165], v[170:173], v[0:3]
	v_mul_f32_e32 v122, v137, v137
	v_fmac_f32_e32 v122, v136, v136
	v_fmac_f32_e32 v122, v138, v138
	v_or_b32_e32 v0, 64, v112
	v_mov_b32_e32 v1, v113
	v_lshl_add_u64 v[0:1], s[16:17], 0, v[0:1]
	v_fmac_f32_e32 v122, v139, v139
	v_or_b32_e32 v112, 0x60, v112
	v_lshl_add_u64 v[112:113], s[16:17], 0, v[112:113]
	s_waitcnt vmcnt(3)
	v_pk_add_f32 v[142:143], v[176:177], v[238:239]
	v_pk_add_f32 v[140:141], v[174:175], v[236:237]
	global_store_dwordx4 v[178:179], v[140:143], off offset:128
	v_cvt_pk_bf16_f32 v2, v140, v141
	v_cvt_pk_bf16_f32 v3, v142, v143
	v_mov_b32_e32 v244, v2
	v_mov_b32_e32 v245, v3
	v_and_b32_e32 v119, 64, v194
	v_xor_b32_e32 v118, 16, v194
	v_add_u32_e32 v119, 64, v119
	v_xor_b32_e32 v120, 32, v194
	v_cmp_lt_i32_e32 vcc, v118, v119
	v_mfma_f32_16x16x32_bf16 v[0:3], v[166:169], v[170:173], v[128:131]
	s_nop 0
	v_cndmask_b32_e32 v121, v194, v118, vcc
	v_cmp_lt_i32_e32 vcc, v120, v119
	v_lshl_or_b32 v118, s18, 2, v144
	v_ashrrev_i32_e32 v119, 31, v118
	v_cndmask_b32_e32 v128, v194, v120, vcc
	v_lshlrev_b32_e32 v120, 2, v121
	v_mul_f32_e32 v121, v125, v125
	v_fmac_f32_e32 v121, v124, v124
	v_fmac_f32_e32 v121, v126, v126
	v_fmac_f32_e32 v121, v127, v127
	v_add_f32_e32 v121, v121, v122
	v_mul_f32_e32 v122, v141, v141
	v_fmac_f32_e32 v122, v140, v140
	v_fmac_f32_e32 v122, v142, v142
	v_fmac_f32_e32 v122, v143, v143
	v_add_f32_e32 v121, v121, v122
	v_lshlrev_b64 v[118:119], 16, v[118:119]
	v_cmp_eq_u32_e32 vcc, 0, v151
	s_waitcnt vmcnt(3)
	v_pk_add_f32 v[122:123], v[132:133], v[240:241]
	s_nop 0
	v_mul_f32_e32 v126, v123, v123
	v_pk_add_f32 v[124:125], v[134:135], v[242:243]
	v_fmac_f32_e32 v126, v122, v122
	v_fmac_f32_e32 v126, v124, v124
	v_fmac_f32_e32 v126, v125, v125
	v_add_f32_e32 v121, v121, v126
	ds_bpermute_b32 v129, v120, v121
	v_lshl_add_u64 v[126:127], s[8:9], 0, v[118:119]
	global_store_dwordx4 v[178:179], v[122:125], off offset:192
	s_waitcnt lgkmcnt(0)
	v_add_f32_e32 v118, v121, v129
	v_lshlrev_b32_e32 v121, 2, v128
	ds_bpermute_b32 v119, v121, v118
	v_cvt_pk_bf16_f32 v122, v122, v123
	v_cvt_pk_bf16_f32 v123, v124, v125
	v_mov_b32_e32 v246, v122
	v_mov_b32_e32 v247, v123
	v_and_b32_e32 v222, 16, v190
	v_mul_u32_u24_e32 v222, 3, v222
	v_lshrrev_b32_e32 v222, 1, v222
	v_mov_b32_e32 v223, 0
	v_lshl_add_u64 v[220:221], v[112:113], 0, v[222:223]
	v_permlane16_swap_b32 v248, v250
	v_permlane16_swap_b32 v249, v251
	v_permlane16_swap_b32 v244, v246
	v_permlane16_swap_b32 v245, v247
	global_store_dwordx4 v[220:221], v[248:251], off offset:-96
	global_store_dwordx4 v[220:221], v[244:247], off offset:-32
	v_lshl_add_u64 v[112:113], v[114:115], 2, v[126:127]
	s_and_saveexec_b64 s[2:3], vcc
	s_cbranch_execz .LBB0_249
	s_waitcnt lgkmcnt(0)
	v_add_f32_e32 v115, v118, v119
	flat_store_dword v[112:113], v115
.LBB0_249:
	s_or_b64 exec, exec, s[2:3]
	v_or_b32_e32 v118, 16, v114
	s_waitcnt lgkmcnt(0)
	v_ashrrev_i32_e32 v119, 31, v118
	v_lshlrev_b64 v[118:119], 10, v[118:119]
	v_lshl_add_u64 v[126:127], v[116:117], 0, v[118:119]
	v_lshl_add_u64 v[118:119], v[126:127], 2, s[90:91]
	global_load_dwordx4 v[228:231], v[118:119], off
	global_load_dwordx4 v[232:235], v[118:119], off offset:64
	global_load_dwordx4 v[236:239], v[118:119], off offset:128
	global_load_dwordx4 v[240:243], v[118:119], off offset:192
	s_waitcnt vmcnt(3)
	v_pk_add_f32 v[108:109], v[108:109], v[228:229]
	v_pk_add_f32 v[110:111], v[110:111], v[230:231]
	v_lshlrev_b64 v[124:125], 1, v[126:127]
	v_mul_f32_e32 v115, v109, v109
	v_lshl_add_u64 v[126:127], s[16:17], 0, v[124:125]
	v_fmac_f32_e32 v115, v108, v108
	global_store_dwordx4 v[118:119], v[108:111], off
	v_cvt_pk_bf16_f32 v122, v108, v109
	v_cvt_pk_bf16_f32 v123, v110, v111
	v_mov_b32_e32 v248, v122
	v_mov_b32_e32 v249, v123
	v_fmac_f32_e32 v115, v110, v110
	v_fmac_f32_e32 v115, v111, v111
	s_waitcnt vmcnt(3)
	v_pk_add_f32 v[106:107], v[106:107], v[234:235]
	v_pk_add_f32 v[104:105], v[104:105], v[232:233]
	global_store_dwordx4 v[118:119], v[104:107], off offset:64
	v_cvt_pk_bf16_f32 v108, v104, v105
	v_or_b32_e32 v110, 32, v124
	v_mov_b32_e32 v111, v125
	v_mul_f32_e32 v105, v105, v105
	v_fmac_f32_e32 v105, v104, v104
	v_lshl_add_u64 v[110:111], s[16:17], 0, v[110:111]
	v_fmac_f32_e32 v105, v106, v106
	v_cvt_pk_bf16_f32 v109, v106, v107
	v_mov_b32_e32 v250, v108
	v_mov_b32_e32 v251, v109
	v_fmac_f32_e32 v105, v107, v107
	v_add_f32_e32 v108, v115, v105
	s_waitcnt vmcnt(3)
	v_pk_add_f32 v[102:103], v[102:103], v[238:239]
	v_pk_add_f32 v[100:101], v[100:101], v[236:237]
	global_store_dwordx4 v[118:119], v[100:103], off offset:128
	v_cvt_pk_bf16_f32 v104, v100, v101
	v_or_b32_e32 v106, 64, v124
	v_mov_b32_e32 v107, v125
	v_mul_f32_e32 v101, v101, v101
	v_fmac_f32_e32 v101, v100, v100
	v_lshl_add_u64 v[106:107], s[16:17], 0, v[106:107]
	v_fmac_f32_e32 v101, v102, v102
	v_cvt_pk_bf16_f32 v105, v102, v103
	v_mov_b32_e32 v244, v104
	v_mov_b32_e32 v245, v105
	v_fmac_f32_e32 v101, v103, v103
	v_add_f32_e32 v104, v108, v101
	v_or_b32_e32 v124, 0x60, v124
	s_waitcnt vmcnt(3)
	v_pk_add_f32 v[98:99], v[98:99], v[242:243]
	v_pk_add_f32 v[96:97], v[96:97], v[240:241]
	global_store_dwordx4 v[118:119], v[96:99], off offset:192
	v_cvt_pk_bf16_f32 v100, v96, v97
	v_lshl_add_u64 v[102:103], s[16:17], 0, v[124:125]
	v_cvt_pk_bf16_f32 v101, v98, v99
	v_mov_b32_e32 v246, v100
	v_mov_b32_e32 v247, v101
	v_and_b32_e32 v222, 16, v190
	v_mul_u32_u24_e32 v222, 3, v222
	v_lshrrev_b32_e32 v222, 1, v222
	v_mov_b32_e32 v223, 0
	v_lshl_add_u64 v[220:221], v[102:103], 0, v[222:223]
	v_permlane16_swap_b32 v248, v250
	v_permlane16_swap_b32 v249, v251
	v_permlane16_swap_b32 v244, v246
	v_permlane16_swap_b32 v245, v247
	global_store_dwordx4 v[220:221], v[248:251], off offset:-96
	global_store_dwordx4 v[220:221], v[244:247], off offset:-32
	v_mul_f32_e32 v97, v97, v97
	v_fmac_f32_e32 v97, v96, v96
	v_fmac_f32_e32 v97, v98, v98
	v_fmac_f32_e32 v97, v99, v99
	v_add_f32_e32 v96, v104, v97
	ds_bpermute_b32 v97, v120, v96
	s_waitcnt lgkmcnt(0)
	v_add_f32_e32 v96, v96, v97
	ds_bpermute_b32 v97, v121, v96
	s_and_saveexec_b64 s[2:3], vcc
	s_cbranch_execz .LBB0_251
	s_waitcnt lgkmcnt(0)
	v_add_f32_e32 v96, v96, v97
	flat_store_dword v[112:113], v96 offset:64
.LBB0_251:
	s_or_b64 exec, exec, s[2:3]
	v_or_b32_e32 v96, 32, v114
	s_waitcnt lgkmcnt(0)
	v_ashrrev_i32_e32 v97, 31, v96
	v_lshlrev_b64 v[96:97], 10, v[96:97]
	v_lshl_add_u64 v[102:103], v[116:117], 0, v[96:97]
	v_lshl_add_u64 v[96:97], v[102:103], 2, s[90:91]
	global_load_dwordx4 v[228:231], v[96:97], off
	global_load_dwordx4 v[232:235], v[96:97], off offset:64
	global_load_dwordx4 v[236:239], v[96:97], off offset:128
	global_load_dwordx4 v[240:243], v[96:97], off offset:192
	s_waitcnt vmcnt(3)
	v_pk_add_f32 v[94:95], v[94:95], v[230:231]
	v_lshlrev_b64 v[100:101], 1, v[102:103]
	v_pk_add_f32 v[92:93], v[92:93], v[228:229]
	v_lshl_add_u64 v[102:103], s[16:17], 0, v[100:101]
	v_cvt_pk_bf16_f32 v98, v92, v93
	global_store_dwordx4 v[96:97], v[92:95], off
	v_cvt_pk_bf16_f32 v99, v94, v95
	v_mov_b32_e32 v248, v98
	v_mov_b32_e32 v249, v99
	v_mul_f32_e32 v98, v93, v93
	v_fmac_f32_e32 v98, v92, v92
	v_fmac_f32_e32 v98, v94, v94
	v_fmac_f32_e32 v98, v95, v95
	s_waitcnt vmcnt(3)
	v_pk_add_f32 v[90:91], v[90:91], v[234:235]
	v_pk_add_f32 v[88:89], v[88:89], v[232:233]
	global_store_dwordx4 v[96:97], v[88:91], off offset:64
	v_cvt_pk_bf16_f32 v92, v88, v89
	v_or_b32_e32 v94, 32, v100
	v_mov_b32_e32 v95, v101
	v_mul_f32_e32 v89, v89, v89
	v_fmac_f32_e32 v89, v88, v88
	v_lshl_add_u64 v[94:95], s[16:17], 0, v[94:95]
	v_fmac_f32_e32 v89, v90, v90
	v_cvt_pk_bf16_f32 v93, v90, v91
	v_mov_b32_e32 v250, v92
	v_mov_b32_e32 v251, v93
	v_fmac_f32_e32 v89, v91, v91
	v_add_f32_e32 v92, v98, v89
	s_waitcnt vmcnt(3)
	v_pk_add_f32 v[86:87], v[86:87], v[238:239]
	v_pk_add_f32 v[84:85], v[84:85], v[236:237]
	global_store_dwordx4 v[96:97], v[84:87], off offset:128
	v_cvt_pk_bf16_f32 v88, v84, v85
	v_or_b32_e32 v90, 64, v100
	v_mov_b32_e32 v91, v101
	v_mul_f32_e32 v85, v85, v85
	v_fmac_f32_e32 v85, v84, v84
	v_lshl_add_u64 v[90:91], s[16:17], 0, v[90:91]
	v_fmac_f32_e32 v85, v86, v86
	v_cvt_pk_bf16_f32 v89, v86, v87
	v_mov_b32_e32 v244, v88
	v_mov_b32_e32 v245, v89
	v_fmac_f32_e32 v85, v87, v87
	v_add_f32_e32 v88, v92, v85
	v_or_b32_e32 v100, 0x60, v100
	s_waitcnt vmcnt(3)
	v_pk_add_f32 v[82:83], v[82:83], v[242:243]
	v_pk_add_f32 v[80:81], v[80:81], v[240:241]
	global_store_dwordx4 v[96:97], v[80:83], off offset:192
	v_cvt_pk_bf16_f32 v84, v80, v81
	v_lshl_add_u64 v[86:87], s[16:17], 0, v[100:101]
	v_cvt_pk_bf16_f32 v85, v82, v83
	v_mov_b32_e32 v246, v84
	v_mov_b32_e32 v247, v85
	v_and_b32_e32 v222, 16, v190
	v_mul_u32_u24_e32 v222, 3, v222
	v_lshrrev_b32_e32 v222, 1, v222
	v_mov_b32_e32 v223, 0
	v_lshl_add_u64 v[220:221], v[86:87], 0, v[222:223]
	v_permlane16_swap_b32 v248, v250
	v_permlane16_swap_b32 v249, v251
	v_permlane16_swap_b32 v244, v246
	v_permlane16_swap_b32 v245, v247
	global_store_dwordx4 v[220:221], v[248:251], off offset:-96
	global_store_dwordx4 v[220:221], v[244:247], off offset:-32
	v_mul_f32_e32 v81, v81, v81
	v_fmac_f32_e32 v81, v80, v80
	v_fmac_f32_e32 v81, v82, v82
	v_fmac_f32_e32 v81, v83, v83
	v_add_f32_e32 v80, v88, v81
	ds_bpermute_b32 v81, v120, v80
	s_waitcnt lgkmcnt(0)
	v_add_f32_e32 v80, v80, v81
	ds_bpermute_b32 v81, v121, v80
	s_and_saveexec_b64 s[2:3], vcc
	s_cbranch_execz .LBB0_253
	s_waitcnt lgkmcnt(0)
	v_add_f32_e32 v80, v80, v81
	flat_store_dword v[112:113], v80 offset:128
.LBB0_253:
	s_or_b64 exec, exec, s[2:3]
	v_or_b32_e32 v80, 48, v114
	s_waitcnt lgkmcnt(0)
	v_ashrrev_i32_e32 v81, 31, v80
	v_lshlrev_b64 v[80:81], 10, v[80:81]
	v_lshl_add_u64 v[86:87], v[116:117], 0, v[80:81]
	v_lshl_add_u64 v[80:81], v[86:87], 2, s[90:91]
	global_load_dwordx4 v[228:231], v[80:81], off
	global_load_dwordx4 v[232:235], v[80:81], off offset:64
	global_load_dwordx4 v[236:239], v[80:81], off offset:128
	global_load_dwordx4 v[240:243], v[80:81], off offset:192
	s_waitcnt vmcnt(3)
	v_pk_add_f32 v[78:79], v[78:79], v[230:231]
	v_lshlrev_b64 v[84:85], 1, v[86:87]
	v_pk_add_f32 v[76:77], v[76:77], v[228:229]
	v_lshl_add_u64 v[86:87], s[16:17], 0, v[84:85]
	v_cvt_pk_bf16_f32 v82, v76, v77
	global_store_dwordx4 v[80:81], v[76:79], off
	v_cvt_pk_bf16_f32 v83, v78, v79
	v_mov_b32_e32 v248, v82
	v_mov_b32_e32 v249, v83
	v_mul_f32_e32 v82, v77, v77
	v_fmac_f32_e32 v82, v76, v76
	v_fmac_f32_e32 v82, v78, v78
	v_fmac_f32_e32 v82, v79, v79
	s_waitcnt vmcnt(3)
	v_pk_add_f32 v[74:75], v[74:75], v[234:235]
	v_pk_add_f32 v[72:73], v[72:73], v[232:233]
	global_store_dwordx4 v[80:81], v[72:75], off offset:64
	v_cvt_pk_bf16_f32 v76, v72, v73
	v_or_b32_e32 v78, 32, v84
	v_mov_b32_e32 v79, v85
	v_mul_f32_e32 v73, v73, v73
	v_fmac_f32_e32 v73, v72, v72
	v_lshl_add_u64 v[78:79], s[16:17], 0, v[78:79]
	v_fmac_f32_e32 v73, v74, v74
	v_cvt_pk_bf16_f32 v77, v74, v75
	v_mov_b32_e32 v250, v76
	v_mov_b32_e32 v251, v77
	v_fmac_f32_e32 v73, v75, v75
	v_add_f32_e32 v76, v82, v73
	s_waitcnt vmcnt(3)
	v_pk_add_f32 v[70:71], v[70:71], v[238:239]
	v_pk_add_f32 v[68:69], v[68:69], v[236:237]
	global_store_dwordx4 v[80:81], v[68:71], off offset:128
	v_cvt_pk_bf16_f32 v72, v68, v69
	v_or_b32_e32 v74, 64, v84
	v_mov_b32_e32 v75, v85
	v_mul_f32_e32 v69, v69, v69
	v_fmac_f32_e32 v69, v68, v68
	v_lshl_add_u64 v[74:75], s[16:17], 0, v[74:75]
	v_fmac_f32_e32 v69, v70, v70
	v_cvt_pk_bf16_f32 v73, v70, v71
	v_mov_b32_e32 v244, v72
	v_mov_b32_e32 v245, v73
	v_fmac_f32_e32 v69, v71, v71
	v_add_f32_e32 v72, v76, v69
	v_or_b32_e32 v84, 0x60, v84
	s_waitcnt vmcnt(3)
	v_pk_add_f32 v[66:67], v[66:67], v[242:243]
	v_pk_add_f32 v[64:65], v[64:65], v[240:241]
	global_store_dwordx4 v[80:81], v[64:67], off offset:192
	v_cvt_pk_bf16_f32 v68, v64, v65
	v_lshl_add_u64 v[70:71], s[16:17], 0, v[84:85]
	v_cvt_pk_bf16_f32 v69, v66, v67
	v_mov_b32_e32 v246, v68
	v_mov_b32_e32 v247, v69
	v_and_b32_e32 v222, 16, v190
	v_mul_u32_u24_e32 v222, 3, v222
	v_lshrrev_b32_e32 v222, 1, v222
	v_mov_b32_e32 v223, 0
	v_lshl_add_u64 v[220:221], v[70:71], 0, v[222:223]
	v_permlane16_swap_b32 v248, v250
	v_permlane16_swap_b32 v249, v251
	v_permlane16_swap_b32 v244, v246
	v_permlane16_swap_b32 v245, v247
	global_store_dwordx4 v[220:221], v[248:251], off offset:-96
	global_store_dwordx4 v[220:221], v[244:247], off offset:-32
	v_mul_f32_e32 v65, v65, v65
	v_fmac_f32_e32 v65, v64, v64
	v_fmac_f32_e32 v65, v66, v66
	v_fmac_f32_e32 v65, v67, v67
	v_add_f32_e32 v64, v72, v65
	ds_bpermute_b32 v65, v120, v64
	s_waitcnt lgkmcnt(0)
	v_add_f32_e32 v64, v64, v65
	ds_bpermute_b32 v65, v121, v64
	s_and_saveexec_b64 s[2:3], vcc
	s_cbranch_execz .LBB0_255
	s_waitcnt lgkmcnt(0)
	v_add_f32_e32 v64, v64, v65
	flat_store_dword v[112:113], v64 offset:192
.LBB0_255:
	s_or_b64 exec, exec, s[2:3]
	v_or_b32_e32 v64, 64, v114
	s_waitcnt lgkmcnt(0)
	v_ashrrev_i32_e32 v65, 31, v64
	v_lshlrev_b64 v[64:65], 10, v[64:65]
	v_lshl_add_u64 v[70:71], v[116:117], 0, v[64:65]
	v_lshl_add_u64 v[64:65], v[70:71], 2, s[90:91]
	global_load_dwordx4 v[228:231], v[64:65], off
	global_load_dwordx4 v[232:235], v[64:65], off offset:64
	global_load_dwordx4 v[236:239], v[64:65], off offset:128
	global_load_dwordx4 v[240:243], v[64:65], off offset:192
	s_waitcnt vmcnt(3)
	v_pk_add_f32 v[62:63], v[62:63], v[230:231]
	v_lshlrev_b64 v[68:69], 1, v[70:71]
	v_pk_add_f32 v[60:61], v[60:61], v[228:229]
	v_lshl_add_u64 v[70:71], s[16:17], 0, v[68:69]
	v_cvt_pk_bf16_f32 v66, v60, v61
	global_store_dwordx4 v[64:65], v[60:63], off
	v_cvt_pk_bf16_f32 v67, v62, v63
	v_mov_b32_e32 v248, v66
	v_mov_b32_e32 v249, v67
	v_mul_f32_e32 v66, v61, v61
	v_fmac_f32_e32 v66, v60, v60
	v_fmac_f32_e32 v66, v62, v62
	v_fmac_f32_e32 v66, v63, v63
	s_waitcnt vmcnt(3)
	v_pk_add_f32 v[58:59], v[58:59], v[234:235]
	v_pk_add_f32 v[56:57], v[56:57], v[232:233]
	global_store_dwordx4 v[64:65], v[56:59], off offset:64
	v_cvt_pk_bf16_f32 v60, v56, v57
	v_or_b32_e32 v62, 32, v68
	v_mov_b32_e32 v63, v69
	v_mul_f32_e32 v57, v57, v57
	v_fmac_f32_e32 v57, v56, v56
	v_lshl_add_u64 v[62:63], s[16:17], 0, v[62:63]
	v_fmac_f32_e32 v57, v58, v58
	v_cvt_pk_bf16_f32 v61, v58, v59
	v_mov_b32_e32 v250, v60
	v_mov_b32_e32 v251, v61
	v_fmac_f32_e32 v57, v59, v59
	v_add_f32_e32 v60, v66, v57
	s_waitcnt vmcnt(3)
	v_pk_add_f32 v[54:55], v[54:55], v[238:239]
	v_pk_add_f32 v[52:53], v[52:53], v[236:237]
	global_store_dwordx4 v[64:65], v[52:55], off offset:128
	v_cvt_pk_bf16_f32 v56, v52, v53
	v_or_b32_e32 v58, 64, v68
	v_mov_b32_e32 v59, v69
	v_mul_f32_e32 v53, v53, v53
	v_fmac_f32_e32 v53, v52, v52
	v_lshl_add_u64 v[58:59], s[16:17], 0, v[58:59]
	v_fmac_f32_e32 v53, v54, v54
	v_cvt_pk_bf16_f32 v57, v54, v55
	v_mov_b32_e32 v244, v56
	v_mov_b32_e32 v245, v57
	v_fmac_f32_e32 v53, v55, v55
	v_add_f32_e32 v56, v60, v53
	v_or_b32_e32 v68, 0x60, v68
	s_waitcnt vmcnt(3)
	v_pk_add_f32 v[50:51], v[50:51], v[242:243]
	v_pk_add_f32 v[48:49], v[48:49], v[240:241]
	global_store_dwordx4 v[64:65], v[48:51], off offset:192
	v_cvt_pk_bf16_f32 v52, v48, v49
	v_lshl_add_u64 v[54:55], s[16:17], 0, v[68:69]
	v_cvt_pk_bf16_f32 v53, v50, v51
	v_mov_b32_e32 v246, v52
	v_mov_b32_e32 v247, v53
	v_and_b32_e32 v222, 16, v190
	v_mul_u32_u24_e32 v222, 3, v222
	v_lshrrev_b32_e32 v222, 1, v222
	v_mov_b32_e32 v223, 0
	v_lshl_add_u64 v[220:221], v[54:55], 0, v[222:223]
	v_permlane16_swap_b32 v248, v250
	v_permlane16_swap_b32 v249, v251
	v_permlane16_swap_b32 v244, v246
	v_permlane16_swap_b32 v245, v247
	global_store_dwordx4 v[220:221], v[248:251], off offset:-96
	global_store_dwordx4 v[220:221], v[244:247], off offset:-32
	v_mul_f32_e32 v49, v49, v49
	v_fmac_f32_e32 v49, v48, v48
	v_fmac_f32_e32 v49, v50, v50
	v_fmac_f32_e32 v49, v51, v51
	v_add_f32_e32 v48, v56, v49
	ds_bpermute_b32 v49, v120, v48
	s_waitcnt lgkmcnt(0)
	v_add_f32_e32 v48, v48, v49
	ds_bpermute_b32 v49, v121, v48
	s_and_saveexec_b64 s[2:3], vcc
	s_cbranch_execz .LBB0_257
	s_waitcnt lgkmcnt(0)
	v_add_f32_e32 v48, v48, v49
	flat_store_dword v[112:113], v48 offset:256
.LBB0_257:
	s_or_b64 exec, exec, s[2:3]
	v_or_b32_e32 v48, 0x50, v114
	s_waitcnt lgkmcnt(0)
	v_ashrrev_i32_e32 v49, 31, v48
	v_lshlrev_b64 v[48:49], 10, v[48:49]
	v_lshl_add_u64 v[54:55], v[116:117], 0, v[48:49]
	v_lshl_add_u64 v[48:49], v[54:55], 2, s[90:91]
	global_load_dwordx4 v[228:231], v[48:49], off
	global_load_dwordx4 v[232:235], v[48:49], off offset:64
	global_load_dwordx4 v[236:239], v[48:49], off offset:128
	global_load_dwordx4 v[240:243], v[48:49], off offset:192
	s_waitcnt vmcnt(3)
	v_pk_add_f32 v[46:47], v[46:47], v[230:231]
	v_lshlrev_b64 v[52:53], 1, v[54:55]
	v_pk_add_f32 v[44:45], v[44:45], v[228:229]
	v_lshl_add_u64 v[54:55], s[16:17], 0, v[52:53]
	v_cvt_pk_bf16_f32 v50, v44, v45
	global_store_dwordx4 v[48:49], v[44:47], off
	v_cvt_pk_bf16_f32 v51, v46, v47
	v_mov_b32_e32 v248, v50
	v_mov_b32_e32 v249, v51
	v_mul_f32_e32 v50, v45, v45
	v_fmac_f32_e32 v50, v44, v44
	v_fmac_f32_e32 v50, v46, v46
	v_fmac_f32_e32 v50, v47, v47
	s_waitcnt vmcnt(3)
	v_pk_add_f32 v[42:43], v[42:43], v[234:235]
	v_pk_add_f32 v[40:41], v[40:41], v[232:233]
	global_store_dwordx4 v[48:49], v[40:43], off offset:64
	v_cvt_pk_bf16_f32 v44, v40, v41
	v_or_b32_e32 v46, 32, v52
	v_mov_b32_e32 v47, v53
	v_mul_f32_e32 v41, v41, v41
	v_fmac_f32_e32 v41, v40, v40
	v_lshl_add_u64 v[46:47], s[16:17], 0, v[46:47]
	v_fmac_f32_e32 v41, v42, v42
	v_cvt_pk_bf16_f32 v45, v42, v43
	v_mov_b32_e32 v250, v44
	v_mov_b32_e32 v251, v45
	v_fmac_f32_e32 v41, v43, v43
	v_add_f32_e32 v44, v50, v41
	s_waitcnt vmcnt(3)
	v_pk_add_f32 v[38:39], v[38:39], v[238:239]
	v_pk_add_f32 v[36:37], v[36:37], v[236:237]
	global_store_dwordx4 v[48:49], v[36:39], off offset:128
	v_cvt_pk_bf16_f32 v40, v36, v37
	v_or_b32_e32 v42, 64, v52
	v_mov_b32_e32 v43, v53
	v_mul_f32_e32 v37, v37, v37
	v_fmac_f32_e32 v37, v36, v36
	v_lshl_add_u64 v[42:43], s[16:17], 0, v[42:43]
	v_fmac_f32_e32 v37, v38, v38
	v_cvt_pk_bf16_f32 v41, v38, v39
	v_mov_b32_e32 v244, v40
	v_mov_b32_e32 v245, v41
	v_fmac_f32_e32 v37, v39, v39
	v_add_f32_e32 v40, v44, v37
	v_or_b32_e32 v52, 0x60, v52
	s_waitcnt vmcnt(3)
	v_pk_add_f32 v[34:35], v[34:35], v[242:243]
	v_pk_add_f32 v[32:33], v[32:33], v[240:241]
	global_store_dwordx4 v[48:49], v[32:35], off offset:192
	v_cvt_pk_bf16_f32 v36, v32, v33
	v_lshl_add_u64 v[38:39], s[16:17], 0, v[52:53]
	v_cvt_pk_bf16_f32 v37, v34, v35
	v_mov_b32_e32 v246, v36
	v_mov_b32_e32 v247, v37
	v_and_b32_e32 v222, 16, v190
	v_mul_u32_u24_e32 v222, 3, v222
	v_lshrrev_b32_e32 v222, 1, v222
	v_mov_b32_e32 v223, 0
	v_lshl_add_u64 v[220:221], v[38:39], 0, v[222:223]
	v_permlane16_swap_b32 v248, v250
	v_permlane16_swap_b32 v249, v251
	v_permlane16_swap_b32 v244, v246
	v_permlane16_swap_b32 v245, v247
	global_store_dwordx4 v[220:221], v[248:251], off offset:-96
	global_store_dwordx4 v[220:221], v[244:247], off offset:-32
	v_mul_f32_e32 v33, v33, v33
	v_fmac_f32_e32 v33, v32, v32
	v_fmac_f32_e32 v33, v34, v34
	v_fmac_f32_e32 v33, v35, v35
	v_add_f32_e32 v32, v40, v33
	ds_bpermute_b32 v33, v120, v32
	s_waitcnt lgkmcnt(0)
	v_add_f32_e32 v32, v32, v33
	ds_bpermute_b32 v33, v121, v32
	s_and_saveexec_b64 s[2:3], vcc
	s_cbranch_execz .LBB0_259
	s_waitcnt lgkmcnt(0)
	v_add_f32_e32 v32, v32, v33
	flat_store_dword v[112:113], v32 offset:320
.LBB0_259:
	s_or_b64 exec, exec, s[2:3]
	v_or_b32_e32 v32, 0x60, v114
	s_waitcnt lgkmcnt(0)
	v_ashrrev_i32_e32 v33, 31, v32
	v_lshlrev_b64 v[32:33], 10, v[32:33]
	v_lshl_add_u64 v[38:39], v[116:117], 0, v[32:33]
	v_lshl_add_u64 v[32:33], v[38:39], 2, s[90:91]
	global_load_dwordx4 v[228:231], v[32:33], off
	global_load_dwordx4 v[232:235], v[32:33], off offset:64
	global_load_dwordx4 v[236:239], v[32:33], off offset:128
	global_load_dwordx4 v[240:243], v[32:33], off offset:192
	s_waitcnt vmcnt(3)
	v_pk_add_f32 v[30:31], v[30:31], v[230:231]
	v_lshlrev_b64 v[36:37], 1, v[38:39]
	v_pk_add_f32 v[28:29], v[28:29], v[228:229]
	v_lshl_add_u64 v[38:39], s[16:17], 0, v[36:37]
	v_cvt_pk_bf16_f32 v34, v28, v29
	global_store_dwordx4 v[32:33], v[28:31], off
	v_cvt_pk_bf16_f32 v35, v30, v31
	v_mov_b32_e32 v248, v34
	v_mov_b32_e32 v249, v35
	v_mul_f32_e32 v34, v29, v29
	v_fmac_f32_e32 v34, v28, v28
	v_fmac_f32_e32 v34, v30, v30
	v_fmac_f32_e32 v34, v31, v31
	s_waitcnt vmcnt(3)
	v_pk_add_f32 v[26:27], v[26:27], v[234:235]
	v_pk_add_f32 v[24:25], v[24:25], v[232:233]
	global_store_dwordx4 v[32:33], v[24:27], off offset:64
	v_cvt_pk_bf16_f32 v28, v24, v25
	v_or_b32_e32 v30, 32, v36
	v_mov_b32_e32 v31, v37
	v_mul_f32_e32 v25, v25, v25
	v_fmac_f32_e32 v25, v24, v24
	v_lshl_add_u64 v[30:31], s[16:17], 0, v[30:31]
	v_fmac_f32_e32 v25, v26, v26
	v_cvt_pk_bf16_f32 v29, v26, v27
	v_mov_b32_e32 v250, v28
	v_mov_b32_e32 v251, v29
	v_fmac_f32_e32 v25, v27, v27
	v_add_f32_e32 v28, v34, v25
	s_waitcnt vmcnt(3)
	v_pk_add_f32 v[22:23], v[22:23], v[238:239]
	v_pk_add_f32 v[20:21], v[20:21], v[236:237]
	global_store_dwordx4 v[32:33], v[20:23], off offset:128
	v_cvt_pk_bf16_f32 v24, v20, v21
	v_or_b32_e32 v26, 64, v36
	v_mov_b32_e32 v27, v37
	v_mul_f32_e32 v21, v21, v21
	v_fmac_f32_e32 v21, v20, v20
	v_lshl_add_u64 v[26:27], s[16:17], 0, v[26:27]
	v_fmac_f32_e32 v21, v22, v22
	v_cvt_pk_bf16_f32 v25, v22, v23
	v_mov_b32_e32 v244, v24
	v_mov_b32_e32 v245, v25
	v_fmac_f32_e32 v21, v23, v23
	v_add_f32_e32 v24, v28, v21
	v_or_b32_e32 v36, 0x60, v36
	s_waitcnt vmcnt(3)
	v_pk_add_f32 v[18:19], v[18:19], v[242:243]
	v_pk_add_f32 v[16:17], v[16:17], v[240:241]
	global_store_dwordx4 v[32:33], v[16:19], off offset:192
	v_cvt_pk_bf16_f32 v20, v16, v17
	v_lshl_add_u64 v[22:23], s[16:17], 0, v[36:37]
	v_cvt_pk_bf16_f32 v21, v18, v19
	v_mov_b32_e32 v246, v20
	v_mov_b32_e32 v247, v21
	v_and_b32_e32 v222, 16, v190
	v_mul_u32_u24_e32 v222, 3, v222
	v_lshrrev_b32_e32 v222, 1, v222
	v_mov_b32_e32 v223, 0
	v_lshl_add_u64 v[220:221], v[22:23], 0, v[222:223]
	v_permlane16_swap_b32 v248, v250
	v_permlane16_swap_b32 v249, v251
	v_permlane16_swap_b32 v244, v246
	v_permlane16_swap_b32 v245, v247
	global_store_dwordx4 v[220:221], v[248:251], off offset:-96
	global_store_dwordx4 v[220:221], v[244:247], off offset:-32
	v_mul_f32_e32 v17, v17, v17
	v_fmac_f32_e32 v17, v16, v16
	v_fmac_f32_e32 v17, v18, v18
	v_fmac_f32_e32 v17, v19, v19
	v_add_f32_e32 v16, v24, v17
	ds_bpermute_b32 v17, v120, v16
	s_waitcnt lgkmcnt(0)
	v_add_f32_e32 v16, v16, v17
	ds_bpermute_b32 v17, v121, v16
	s_and_saveexec_b64 s[2:3], vcc
	s_cbranch_execz .LBB0_261
	s_waitcnt lgkmcnt(0)
	v_add_f32_e32 v16, v16, v17
	flat_store_dword v[112:113], v16 offset:384
.LBB0_261:
	s_or_b64 exec, exec, s[2:3]
	v_or_b32_e32 v16, 0x70, v114
	s_waitcnt lgkmcnt(0)
	v_ashrrev_i32_e32 v17, 31, v16
	v_lshlrev_b64 v[16:17], 10, v[16:17]
	v_lshl_add_u64 v[22:23], v[116:117], 0, v[16:17]
	v_lshl_add_u64 v[16:17], v[22:23], 2, s[90:91]
	global_load_dwordx4 v[228:231], v[16:17], off
	global_load_dwordx4 v[232:235], v[16:17], off offset:64
	global_load_dwordx4 v[236:239], v[16:17], off offset:128
	global_load_dwordx4 v[240:243], v[16:17], off offset:192
	s_waitcnt vmcnt(3)
	v_pk_add_f32 v[14:15], v[14:15], v[230:231]
	v_lshlrev_b64 v[20:21], 1, v[22:23]
	v_pk_add_f32 v[12:13], v[12:13], v[228:229]
	v_lshl_add_u64 v[22:23], s[16:17], 0, v[20:21]
	v_cvt_pk_bf16_f32 v18, v12, v13
	global_store_dwordx4 v[16:17], v[12:15], off
	v_cvt_pk_bf16_f32 v19, v14, v15
	v_mov_b32_e32 v248, v18
	v_mov_b32_e32 v249, v19
	v_mul_f32_e32 v18, v13, v13
	v_fmac_f32_e32 v18, v12, v12
	v_fmac_f32_e32 v18, v14, v14
	v_fmac_f32_e32 v18, v15, v15
	s_waitcnt vmcnt(3)
	v_pk_add_f32 v[10:11], v[10:11], v[234:235]
	v_pk_add_f32 v[8:9], v[8:9], v[232:233]
	global_store_dwordx4 v[16:17], v[8:11], off offset:64
	v_cvt_pk_bf16_f32 v12, v8, v9
	v_or_b32_e32 v14, 32, v20
	v_mov_b32_e32 v15, v21
	v_mul_f32_e32 v9, v9, v9
	v_fmac_f32_e32 v9, v8, v8
	v_lshl_add_u64 v[14:15], s[16:17], 0, v[14:15]
	v_fmac_f32_e32 v9, v10, v10
	v_cvt_pk_bf16_f32 v13, v10, v11
	v_mov_b32_e32 v250, v12
	v_mov_b32_e32 v251, v13
	v_fmac_f32_e32 v9, v11, v11
	v_add_f32_e32 v12, v18, v9
	s_waitcnt vmcnt(3)
	v_pk_add_f32 v[6:7], v[6:7], v[238:239]
	v_pk_add_f32 v[4:5], v[4:5], v[236:237]
	global_store_dwordx4 v[16:17], v[4:7], off offset:128
	v_cvt_pk_bf16_f32 v8, v4, v5
	v_or_b32_e32 v10, 64, v20
	v_mov_b32_e32 v11, v21
	v_mul_f32_e32 v5, v5, v5
	v_fmac_f32_e32 v5, v4, v4
	v_lshl_add_u64 v[10:11], s[16:17], 0, v[10:11]
	v_fmac_f32_e32 v5, v6, v6
	v_cvt_pk_bf16_f32 v9, v6, v7
	v_mov_b32_e32 v244, v8
	v_mov_b32_e32 v245, v9
	v_fmac_f32_e32 v5, v7, v7
	v_add_f32_e32 v8, v12, v5
	v_or_b32_e32 v20, 0x60, v20
	s_waitcnt vmcnt(3)
	v_pk_add_f32 v[2:3], v[2:3], v[242:243]
	v_pk_add_f32 v[0:1], v[0:1], v[240:241]
	global_store_dwordx4 v[16:17], v[0:3], off offset:192
	v_cvt_pk_bf16_f32 v4, v0, v1
	v_lshl_add_u64 v[6:7], s[16:17], 0, v[20:21]
	v_cvt_pk_bf16_f32 v5, v2, v3
	v_mov_b32_e32 v246, v4
	v_mov_b32_e32 v247, v5
	v_and_b32_e32 v222, 16, v190
	v_mul_u32_u24_e32 v222, 3, v222
	v_lshrrev_b32_e32 v222, 1, v222
	v_mov_b32_e32 v223, 0
	v_lshl_add_u64 v[220:221], v[6:7], 0, v[222:223]
	v_permlane16_swap_b32 v248, v250
	v_permlane16_swap_b32 v249, v251
	v_permlane16_swap_b32 v244, v246
	v_permlane16_swap_b32 v245, v247
	global_store_dwordx4 v[220:221], v[248:251], off offset:-96
	global_store_dwordx4 v[220:221], v[244:247], off offset:-32
	v_mul_f32_e32 v1, v1, v1
	v_fmac_f32_e32 v1, v0, v0
	v_fmac_f32_e32 v1, v2, v2
	v_fmac_f32_e32 v1, v3, v3
	v_add_f32_e32 v0, v8, v1
	ds_bpermute_b32 v1, v120, v0
	s_waitcnt lgkmcnt(0)
	v_add_f32_e32 v0, v0, v1
	ds_bpermute_b32 v1, v121, v0
	s_and_saveexec_b64 s[2:3], vcc
	s_cbranch_execz .LBB0_244
	s_waitcnt lgkmcnt(0)
	v_add_f32_e32 v0, v0, v1
	flat_store_dword v[112:113], v0 offset:448
	s_branch .LBB0_244

.LBB0_505:
	s_andn2_b64 vcc, exec, s[2:3]
	s_cbranch_vccnz .LBB0_507
	v_lshl_add_u64 v[142:143], v[136:137], 1, s[16:17]
	v_cvt_pk_bf16_f32 v140, v120, v121
	v_cvt_pk_bf16_f32 v141, v122, v123
	v_mov_b32_e32 v248, v140
	v_mov_b32_e32 v249, v141

.LBB0_509:
	s_andn2_b64 vcc, exec, s[2:3]
	v_lshlrev_b64 v[136:137], 1, v[136:137]
	s_cbranch_vccnz .LBB0_511
	v_or_b32_e32 v142, 32, v136
	v_mov_b32_e32 v143, v137
	v_lshl_add_u64 v[142:143], s[16:17], 0, v[142:143]
	v_cvt_pk_bf16_f32 v140, v124, v125
	v_cvt_pk_bf16_f32 v141, v126, v127
	v_mov_b32_e32 v250, v140
	v_mov_b32_e32 v251, v141

.LBB0_513:
	s_andn2_b64 vcc, exec, s[2:3]
	s_cbranch_vccnz .LBB0_515
	v_or_b32_e32 v142, 64, v136
	v_mov_b32_e32 v143, v137
	v_lshl_add_u64 v[142:143], s[16:17], 0, v[142:143]
	v_cvt_pk_bf16_f32 v140, v116, v117
	v_cvt_pk_bf16_f32 v141, v118, v119
	v_mov_b32_e32 v244, v140
	v_mov_b32_e32 v245, v141

.LBB0_517:
	s_andn2_b64 vcc, exec, s[2:3]
	s_cbranch_vccnz .LBB0_519
	v_or_b32_e32 v136, 0x60, v136
	v_lshl_add_u64 v[134:135], s[16:17], 0, v[136:137]
	v_cvt_pk_bf16_f32 v132, v112, v113
	v_cvt_pk_bf16_f32 v133, v114, v115
	v_mov_b32_e32 v246, v132
	v_mov_b32_e32 v247, v133
	v_and_b32_e32 v226, 16, v190
	v_mul_u32_u24_e32 v226, 3, v226
	v_lshrrev_b32_e32 v226, 1, v226
	v_mov_b32_e32 v227, 0
	v_lshl_add_u64 v[224:225], v[134:135], 0, v[226:227]
	v_permlane16_swap_b32 v248, v250
	v_permlane16_swap_b32 v249, v251
	v_permlane16_swap_b32 v244, v246
	v_permlane16_swap_b32 v245, v247
	global_store_dwordx4 v[224:225], v[248:251], off offset:-96
	global_store_dwordx4 v[224:225], v[244:247], off offset:-32

.LBB0_523:
	s_andn2_b64 vcc, exec, s[2:3]
	s_cbranch_vccnz .LBB0_525
	v_lshl_add_u64 v[124:125], v[118:119], 1, s[16:17]
	v_cvt_pk_bf16_f32 v122, v108, v109
	v_cvt_pk_bf16_f32 v123, v110, v111
	v_mov_b32_e32 v248, v122
	v_mov_b32_e32 v249, v123

.LBB0_527:
	s_andn2_b64 vcc, exec, s[2:3]
	v_lshlrev_b64 v[118:119], 1, v[118:119]
	s_cbranch_vccnz .LBB0_529
	v_or_b32_e32 v124, 32, v118
	v_mov_b32_e32 v125, v119
	v_lshl_add_u64 v[124:125], s[16:17], 0, v[124:125]
	v_cvt_pk_bf16_f32 v122, v104, v105
	v_cvt_pk_bf16_f32 v123, v106, v107
	v_mov_b32_e32 v250, v122
	v_mov_b32_e32 v251, v123

.LBB0_531:
	s_andn2_b64 vcc, exec, s[2:3]
	s_cbranch_vccnz .LBB0_533
	v_or_b32_e32 v124, 64, v118
	v_mov_b32_e32 v125, v119
	v_lshl_add_u64 v[124:125], s[16:17], 0, v[124:125]
	v_cvt_pk_bf16_f32 v122, v100, v101
	v_cvt_pk_bf16_f32 v123, v102, v103
	v_mov_b32_e32 v244, v122
	v_mov_b32_e32 v245, v123

.LBB0_535:
	s_andn2_b64 vcc, exec, s[2:3]
	s_cbranch_vccnz .LBB0_537
	v_or_b32_e32 v118, 0x60, v118
	v_lshl_add_u64 v[116:117], s[16:17], 0, v[118:119]
	v_cvt_pk_bf16_f32 v114, v96, v97
	v_cvt_pk_bf16_f32 v115, v98, v99
	v_mov_b32_e32 v246, v114
	v_mov_b32_e32 v247, v115
	v_and_b32_e32 v226, 16, v190
	v_mul_u32_u24_e32 v226, 3, v226
	v_lshrrev_b32_e32 v226, 1, v226
	v_mov_b32_e32 v227, 0
	v_lshl_add_u64 v[224:225], v[116:117], 0, v[226:227]
	v_permlane16_swap_b32 v248, v250
	v_permlane16_swap_b32 v249, v251
	v_permlane16_swap_b32 v244, v246
	v_permlane16_swap_b32 v245, v247
	global_store_dwordx4 v[224:225], v[248:251], off offset:-96
	global_store_dwordx4 v[224:225], v[244:247], off offset:-32

.LBB0_541:
	s_andn2_b64 vcc, exec, s[2:3]
	s_cbranch_vccnz .LBB0_543
	v_lshl_add_u64 v[104:105], v[100:101], 1, s[16:17]
	v_cvt_pk_bf16_f32 v102, v92, v93
	v_cvt_pk_bf16_f32 v103, v94, v95
	v_mov_b32_e32 v248, v102
	v_mov_b32_e32 v249, v103

.LBB0_545:
	s_andn2_b64 vcc, exec, s[2:3]
	v_lshlrev_b64 v[100:101], 1, v[100:101]
	s_cbranch_vccnz .LBB0_547
	v_or_b32_e32 v104, 32, v100
	v_mov_b32_e32 v105, v101
	v_lshl_add_u64 v[104:105], s[16:17], 0, v[104:105]
	v_cvt_pk_bf16_f32 v102, v88, v89
	v_cvt_pk_bf16_f32 v103, v90, v91
	v_mov_b32_e32 v250, v102
	v_mov_b32_e32 v251, v103

.LBB0_549:
	s_andn2_b64 vcc, exec, s[2:3]
	s_cbranch_vccnz .LBB0_551
	v_or_b32_e32 v104, 64, v100
	v_mov_b32_e32 v105, v101
	v_lshl_add_u64 v[104:105], s[16:17], 0, v[104:105]
	v_cvt_pk_bf16_f32 v102, v84, v85
	v_cvt_pk_bf16_f32 v103, v86, v87
	v_mov_b32_e32 v244, v102
	v_mov_b32_e32 v245, v103

.LBB0_553:
	s_andn2_b64 vcc, exec, s[2:3]
	s_cbranch_vccnz .LBB0_555
	v_or_b32_e32 v100, 0x60, v100
	v_lshl_add_u64 v[98:99], s[16:17], 0, v[100:101]
	v_cvt_pk_bf16_f32 v96, v80, v81
	v_cvt_pk_bf16_f32 v97, v82, v83
	v_mov_b32_e32 v246, v96
	v_mov_b32_e32 v247, v97
	v_and_b32_e32 v226, 16, v190
	v_mul_u32_u24_e32 v226, 3, v226
	v_lshrrev_b32_e32 v226, 1, v226
	v_mov_b32_e32 v227, 0
	v_lshl_add_u64 v[224:225], v[98:99], 0, v[226:227]
	v_permlane16_swap_b32 v248, v250
	v_permlane16_swap_b32 v249, v251
	v_permlane16_swap_b32 v244, v246
	v_permlane16_swap_b32 v245, v247
	global_store_dwordx4 v[224:225], v[248:251], off offset:-96
	global_store_dwordx4 v[224:225], v[244:247], off offset:-32

.LBB0_559:
	s_andn2_b64 vcc, exec, s[2:3]
	s_cbranch_vccnz .LBB0_561
	v_lshl_add_u64 v[88:89], v[84:85], 1, s[16:17]
	v_cvt_pk_bf16_f32 v86, v76, v77
	v_cvt_pk_bf16_f32 v87, v78, v79
	v_mov_b32_e32 v248, v86
	v_mov_b32_e32 v249, v87

.LBB0_563:
	s_andn2_b64 vcc, exec, s[2:3]
	v_lshlrev_b64 v[84:85], 1, v[84:85]
	s_cbranch_vccnz .LBB0_565
	v_or_b32_e32 v88, 32, v84
	v_mov_b32_e32 v89, v85
	v_lshl_add_u64 v[88:89], s[16:17], 0, v[88:89]
	v_cvt_pk_bf16_f32 v86, v72, v73
	v_cvt_pk_bf16_f32 v87, v74, v75
	v_mov_b32_e32 v250, v86
	v_mov_b32_e32 v251, v87

.LBB0_567:
	s_andn2_b64 vcc, exec, s[2:3]
	s_cbranch_vccnz .LBB0_569
	v_or_b32_e32 v88, 64, v84
	v_mov_b32_e32 v89, v85
	v_lshl_add_u64 v[88:89], s[16:17], 0, v[88:89]
	v_cvt_pk_bf16_f32 v86, v68, v69
	v_cvt_pk_bf16_f32 v87, v70, v71
	v_mov_b32_e32 v244, v86
	v_mov_b32_e32 v245, v87

.LBB0_571:
	s_andn2_b64 vcc, exec, s[2:3]
	s_cbranch_vccnz .LBB0_573
	v_or_b32_e32 v84, 0x60, v84
	v_lshl_add_u64 v[82:83], s[16:17], 0, v[84:85]
	v_cvt_pk_bf16_f32 v80, v64, v65
	v_cvt_pk_bf16_f32 v81, v66, v67
	v_mov_b32_e32 v246, v80
	v_mov_b32_e32 v247, v81
	v_and_b32_e32 v226, 16, v190
	v_mul_u32_u24_e32 v226, 3, v226
	v_lshrrev_b32_e32 v226, 1, v226
	v_mov_b32_e32 v227, 0
	v_lshl_add_u64 v[224:225], v[82:83], 0, v[226:227]
	v_permlane16_swap_b32 v248, v250
	v_permlane16_swap_b32 v249, v251
	v_permlane16_swap_b32 v244, v246
	v_permlane16_swap_b32 v245, v247
	global_store_dwordx4 v[224:225], v[248:251], off offset:-96
	global_store_dwordx4 v[224:225], v[244:247], off offset:-32

.LBB0_577:
	s_andn2_b64 vcc, exec, s[2:3]
	s_cbranch_vccnz .LBB0_579
	v_lshl_add_u64 v[72:73], v[68:69], 1, s[16:17]
	v_cvt_pk_bf16_f32 v70, v60, v61
	v_cvt_pk_bf16_f32 v71, v62, v63
	v_mov_b32_e32 v248, v70
	v_mov_b32_e32 v249, v71

.LBB0_581:
	s_andn2_b64 vcc, exec, s[2:3]
	v_lshlrev_b64 v[68:69], 1, v[68:69]
	s_cbranch_vccnz .LBB0_583
	v_or_b32_e32 v72, 32, v68
	v_mov_b32_e32 v73, v69
	v_lshl_add_u64 v[72:73], s[16:17], 0, v[72:73]
	v_cvt_pk_bf16_f32 v70, v56, v57
	v_cvt_pk_bf16_f32 v71, v58, v59
	v_mov_b32_e32 v250, v70
	v_mov_b32_e32 v251, v71

.LBB0_585:
	s_andn2_b64 vcc, exec, s[2:3]
	s_cbranch_vccnz .LBB0_587
	v_or_b32_e32 v72, 64, v68
	v_mov_b32_e32 v73, v69
	v_lshl_add_u64 v[72:73], s[16:17], 0, v[72:73]
	v_cvt_pk_bf16_f32 v70, v52, v53
	v_cvt_pk_bf16_f32 v71, v54, v55
	v_mov_b32_e32 v244, v70
	v_mov_b32_e32 v245, v71

.LBB0_589:
	s_andn2_b64 vcc, exec, s[2:3]
	s_cbranch_vccnz .LBB0_591
	v_or_b32_e32 v68, 0x60, v68
	v_lshl_add_u64 v[66:67], s[16:17], 0, v[68:69]
	v_cvt_pk_bf16_f32 v64, v48, v49
	v_cvt_pk_bf16_f32 v65, v50, v51
	v_mov_b32_e32 v246, v64
	v_mov_b32_e32 v247, v65
	v_and_b32_e32 v226, 16, v190
	v_mul_u32_u24_e32 v226, 3, v226
	v_lshrrev_b32_e32 v226, 1, v226
	v_mov_b32_e32 v227, 0
	v_lshl_add_u64 v[224:225], v[66:67], 0, v[226:227]
	v_permlane16_swap_b32 v248, v250
	v_permlane16_swap_b32 v249, v251
	v_permlane16_swap_b32 v244, v246
	v_permlane16_swap_b32 v245, v247
	global_store_dwordx4 v[224:225], v[248:251], off offset:-96
	global_store_dwordx4 v[224:225], v[244:247], off offset:-32

.LBB0_595:
	s_andn2_b64 vcc, exec, s[2:3]
	s_cbranch_vccnz .LBB0_597
	v_lshl_add_u64 v[56:57], v[52:53], 1, s[16:17]
	v_cvt_pk_bf16_f32 v54, v44, v45
	v_cvt_pk_bf16_f32 v55, v46, v47
	v_mov_b32_e32 v248, v54
	v_mov_b32_e32 v249, v55

.LBB0_599:
	s_andn2_b64 vcc, exec, s[2:3]
	v_lshlrev_b64 v[52:53], 1, v[52:53]
	s_cbranch_vccnz .LBB0_601
	v_or_b32_e32 v56, 32, v52
	v_mov_b32_e32 v57, v53
	v_lshl_add_u64 v[56:57], s[16:17], 0, v[56:57]
	v_cvt_pk_bf16_f32 v54, v40, v41
	v_cvt_pk_bf16_f32 v55, v42, v43
	v_mov_b32_e32 v250, v54
	v_mov_b32_e32 v251, v55

.LBB0_603:
	s_andn2_b64 vcc, exec, s[2:3]
	s_cbranch_vccnz .LBB0_605
	v_or_b32_e32 v56, 64, v52
	v_mov_b32_e32 v57, v53
	v_lshl_add_u64 v[56:57], s[16:17], 0, v[56:57]
	v_cvt_pk_bf16_f32 v54, v36, v37
	v_cvt_pk_bf16_f32 v55, v38, v39
	v_mov_b32_e32 v244, v54
	v_mov_b32_e32 v245, v55

.LBB0_607:
	s_andn2_b64 vcc, exec, s[2:3]
	s_cbranch_vccnz .LBB0_609
	v_or_b32_e32 v52, 0x60, v52
	v_lshl_add_u64 v[50:51], s[16:17], 0, v[52:53]
	v_cvt_pk_bf16_f32 v48, v32, v33
	v_cvt_pk_bf16_f32 v49, v34, v35
	v_mov_b32_e32 v246, v48
	v_mov_b32_e32 v247, v49
	v_and_b32_e32 v226, 16, v190
	v_mul_u32_u24_e32 v226, 3, v226
	v_lshrrev_b32_e32 v226, 1, v226
	v_mov_b32_e32 v227, 0
	v_lshl_add_u64 v[224:225], v[50:51], 0, v[226:227]
	v_permlane16_swap_b32 v248, v250
	v_permlane16_swap_b32 v249, v251
	v_permlane16_swap_b32 v244, v246
	v_permlane16_swap_b32 v245, v247
	global_store_dwordx4 v[224:225], v[248:251], off offset:-96
	global_store_dwordx4 v[224:225], v[244:247], off offset:-32

.LBB0_613:
	s_andn2_b64 vcc, exec, s[2:3]
	s_cbranch_vccnz .LBB0_615
	v_lshl_add_u64 v[40:41], v[36:37], 1, s[16:17]
	v_cvt_pk_bf16_f32 v38, v28, v29
	v_cvt_pk_bf16_f32 v39, v30, v31
	v_mov_b32_e32 v248, v38
	v_mov_b32_e32 v249, v39

.LBB0_617:
	s_andn2_b64 vcc, exec, s[2:3]
	v_lshlrev_b64 v[36:37], 1, v[36:37]
	s_cbranch_vccnz .LBB0_619
	v_or_b32_e32 v40, 32, v36
	v_mov_b32_e32 v41, v37
	v_lshl_add_u64 v[40:41], s[16:17], 0, v[40:41]
	v_cvt_pk_bf16_f32 v38, v24, v25
	v_cvt_pk_bf16_f32 v39, v26, v27
	v_mov_b32_e32 v250, v38
	v_mov_b32_e32 v251, v39

.LBB0_621:
	s_andn2_b64 vcc, exec, s[2:3]
	s_cbranch_vccnz .LBB0_623
	v_or_b32_e32 v40, 64, v36
	v_mov_b32_e32 v41, v37
	v_lshl_add_u64 v[40:41], s[16:17], 0, v[40:41]
	v_cvt_pk_bf16_f32 v38, v20, v21
	v_cvt_pk_bf16_f32 v39, v22, v23
	v_mov_b32_e32 v244, v38
	v_mov_b32_e32 v245, v39

.LBB0_625:
	s_andn2_b64 vcc, exec, s[2:3]
	s_cbranch_vccnz .LBB0_627
	v_or_b32_e32 v36, 0x60, v36
	v_lshl_add_u64 v[34:35], s[16:17], 0, v[36:37]
	v_cvt_pk_bf16_f32 v32, v16, v17
	v_cvt_pk_bf16_f32 v33, v18, v19
	v_mov_b32_e32 v246, v32
	v_mov_b32_e32 v247, v33
	v_and_b32_e32 v226, 16, v190
	v_mul_u32_u24_e32 v226, 3, v226
	v_lshrrev_b32_e32 v226, 1, v226
	v_mov_b32_e32 v227, 0
	v_lshl_add_u64 v[224:225], v[34:35], 0, v[226:227]
	v_permlane16_swap_b32 v248, v250
	v_permlane16_swap_b32 v249, v251
	v_permlane16_swap_b32 v244, v246
	v_permlane16_swap_b32 v245, v247
	global_store_dwordx4 v[224:225], v[248:251], off offset:-96
	global_store_dwordx4 v[224:225], v[244:247], off offset:-32

.LBB0_631:
	s_andn2_b64 vcc, exec, s[2:3]
	s_cbranch_vccnz .LBB0_633
	v_lshl_add_u64 v[24:25], v[20:21], 1, s[16:17]
	v_cvt_pk_bf16_f32 v22, v12, v13
	v_cvt_pk_bf16_f32 v23, v14, v15
	v_mov_b32_e32 v248, v22
	v_mov_b32_e32 v249, v23

.LBB0_635:
	s_andn2_b64 vcc, exec, s[2:3]
	v_lshlrev_b64 v[20:21], 1, v[20:21]
	s_cbranch_vccnz .LBB0_637
	v_or_b32_e32 v24, 32, v20
	v_mov_b32_e32 v25, v21
	v_lshl_add_u64 v[24:25], s[16:17], 0, v[24:25]
	v_cvt_pk_bf16_f32 v22, v8, v9
	v_cvt_pk_bf16_f32 v23, v10, v11
	v_mov_b32_e32 v250, v22
	v_mov_b32_e32 v251, v23

.LBB0_639:
	s_andn2_b64 vcc, exec, s[2:3]
	s_cbranch_vccnz .LBB0_641
	v_or_b32_e32 v24, 64, v20
	v_mov_b32_e32 v25, v21
	v_lshl_add_u64 v[24:25], s[16:17], 0, v[24:25]
	v_cvt_pk_bf16_f32 v22, v4, v5
	v_cvt_pk_bf16_f32 v23, v6, v7
	v_mov_b32_e32 v244, v22
	v_mov_b32_e32 v245, v23

.LBB0_643:
	s_andn2_b64 vcc, exec, s[2:3]
	s_cbranch_vccnz .LBB0_645
	v_or_b32_e32 v20, 0x60, v20
	v_lshl_add_u64 v[18:19], s[16:17], 0, v[20:21]
	v_cvt_pk_bf16_f32 v16, v0, v1
	v_cvt_pk_bf16_f32 v17, v2, v3
	v_mov_b32_e32 v246, v16
	v_mov_b32_e32 v247, v17
	v_and_b32_e32 v226, 16, v190
	v_mul_u32_u24_e32 v226, 3, v226
	v_lshrrev_b32_e32 v226, 1, v226
	v_mov_b32_e32 v227, 0
	v_lshl_add_u64 v[224:225], v[18:19], 0, v[226:227]
	v_permlane16_swap_b32 v248, v250
	v_permlane16_swap_b32 v249, v251
	v_permlane16_swap_b32 v244, v246
	v_permlane16_swap_b32 v245, v247
	global_store_dwordx4 v[224:225], v[248:251], off offset:-96
	global_store_dwordx4 v[224:225], v[244:247], off offset:-32
